# v43: gdn_prep KK^T/QK^T stage epilogue rewritten by hand (pipelined b128 reads of gcs/betas, selects instead of per-element branches)
# speedup vs baseline: 1.1977x; 1.0054x over previous
.LBB0_2882:
	s_or_b64 exec, exec, s[0:1]
	s_mul_i32 s29, s72, 0xa000
	s_mul_hi_i32 s28, s72, 0xa000
	s_add_u32 s30, s60, s29
	s_addc_u32 s31, s61, s28
	s_add_u32 s34, s30, 0x6000
	s_addc_u32 s35, s31, 0
	s_ashr_i32 s73, s72, 31
	v_or_b32_e32 v45, v41, v75
	v_lshl_or_b32 v41, v20, 2, v81
	v_lshl_or_b32 v43, v45, 2, v81
	v_lshl_or_b32 v44, v45, 2, v95
	ds_read_b32 v46, v41
	ds_read_b128 v[48:51], v43
	ds_read_b128 v[52:55], v43 offset:32
	ds_read_b128 v[56:59], v43 offset:64
	ds_read_b128 v[60:63], v43 offset:96
	ds_read_b128 v[184:187], v44
	ds_read_b128 v[188:191], v44 offset:32
	ds_read_b128 v[192:195], v44 offset:64
	ds_read_b128 v[196:199], v44 offset:96
	v_lshlrev_b32_e32 v64, 1, v20
	v_lshl_or_b32 v65, v45, 7, v64
	v_lshlrev_b32_e32 v66, 2, v20
	v_lshl_or_b32 v66, v45, 8, v66
	v_sub_u32_e32 v67, v20, v45
	s_cmp_lg_u64 s[16:17], 0
	s_cbranch_scc0 .Lkk_p0
	s_waitcnt lgkmcnt(7)
	v_sub_f32_e32 v200, v48, v46
	v_sub_f32_e32 v201, v49, v46
	v_sub_f32_e32 v202, v50, v46
	v_sub_f32_e32 v203, v51, v46
	v_mul_f32_e32 v200, 0x3fb8aa3b, v200
	v_mul_f32_e32 v201, 0x3fb8aa3b, v201
	v_mul_f32_e32 v202, 0x3fb8aa3b, v202
	v_mul_f32_e32 v203, 0x3fb8aa3b, v203
	v_exp_f32_e32 v200, v200
	v_exp_f32_e32 v201, v201
	v_exp_f32_e32 v202, v202
	v_exp_f32_e32 v203, v203
	v_cmp_ge_i32_e64 s[28:29], 0, v67
	v_cmp_ge_i32_e64 s[36:37], 1, v67
	v_cmp_ge_i32_e64 s[40:41], 2, v67
	v_cmp_ge_i32_e64 s[46:47], 3, v67
	v_mul_f32_e32 v200, v0, v200
	v_mul_f32_e32 v201, v1, v201
	v_mul_f32_e32 v202, v2, v202
	v_mul_f32_e32 v203, v3, v203
	v_cndmask_b32_e64 v200, 0, v200, s[28:29]
	v_cndmask_b32_e64 v201, 0, v201, s[36:37]
	v_cndmask_b32_e64 v202, 0, v202, s[40:41]
	v_cndmask_b32_e64 v203, 0, v203, s[46:47]
	v_cvt_pk_bf16_f32 v204, v200, v201
	v_cvt_pk_bf16_f32 v205, v202, v203
	global_store_short v65, v204, s[34:35]
	global_store_short_d16_hi v65, v204, s[34:35] offset:128
	global_store_short v65, v205, s[34:35] offset:256
	global_store_short_d16_hi v65, v205, s[34:35] offset:384
	s_waitcnt lgkmcnt(6)
	v_sub_f32_e32 v200, v52, v46
	v_sub_f32_e32 v201, v53, v46
	v_sub_f32_e32 v202, v54, v46
	v_sub_f32_e32 v203, v55, v46
	v_mul_f32_e32 v200, 0x3fb8aa3b, v200
	v_mul_f32_e32 v201, 0x3fb8aa3b, v201
	v_mul_f32_e32 v202, 0x3fb8aa3b, v202
	v_mul_f32_e32 v203, 0x3fb8aa3b, v203
	v_exp_f32_e32 v200, v200
	v_exp_f32_e32 v201, v201
	v_exp_f32_e32 v202, v202
	v_exp_f32_e32 v203, v203
	v_cmp_ge_i32_e64 s[28:29], 8, v67
	v_cmp_ge_i32_e64 s[36:37], 9, v67
	v_cmp_ge_i32_e64 s[40:41], 10, v67
	v_cmp_ge_i32_e64 s[46:47], 11, v67
	v_mul_f32_e32 v200, v4, v200
	v_mul_f32_e32 v201, v5, v201
	v_mul_f32_e32 v202, v6, v202
	v_mul_f32_e32 v203, v7, v203
	v_cndmask_b32_e64 v200, 0, v200, s[28:29]
	v_cndmask_b32_e64 v201, 0, v201, s[36:37]
	v_cndmask_b32_e64 v202, 0, v202, s[40:41]
	v_cndmask_b32_e64 v203, 0, v203, s[46:47]
	v_cvt_pk_bf16_f32 v204, v200, v201
	v_cvt_pk_bf16_f32 v205, v202, v203
	global_store_short v65, v204, s[34:35] offset:1024
	global_store_short_d16_hi v65, v204, s[34:35] offset:1152
	global_store_short v65, v205, s[34:35] offset:1280
	global_store_short_d16_hi v65, v205, s[34:35] offset:1408
	s_waitcnt lgkmcnt(5)
	v_sub_f32_e32 v200, v56, v46
	v_sub_f32_e32 v201, v57, v46
	v_sub_f32_e32 v202, v58, v46
	v_sub_f32_e32 v203, v59, v46
	v_mul_f32_e32 v200, 0x3fb8aa3b, v200
	v_mul_f32_e32 v201, 0x3fb8aa3b, v201
	v_mul_f32_e32 v202, 0x3fb8aa3b, v202
	v_mul_f32_e32 v203, 0x3fb8aa3b, v203
	v_exp_f32_e32 v200, v200
	v_exp_f32_e32 v201, v201
	v_exp_f32_e32 v202, v202
	v_exp_f32_e32 v203, v203
	v_cmp_ge_i32_e64 s[28:29], 16, v67
	v_cmp_ge_i32_e64 s[36:37], 17, v67
	v_cmp_ge_i32_e64 s[40:41], 18, v67
	v_cmp_ge_i32_e64 s[46:47], 19, v67
	v_mul_f32_e32 v200, v8, v200
	v_mul_f32_e32 v201, v9, v201
	v_mul_f32_e32 v202, v10, v202
	v_mul_f32_e32 v203, v11, v203
	v_cndmask_b32_e64 v200, 0, v200, s[28:29]
	v_cndmask_b32_e64 v201, 0, v201, s[36:37]
	v_cndmask_b32_e64 v202, 0, v202, s[40:41]
	v_cndmask_b32_e64 v203, 0, v203, s[46:47]
	v_cvt_pk_bf16_f32 v204, v200, v201
	v_cvt_pk_bf16_f32 v205, v202, v203
	global_store_short v65, v204, s[34:35] offset:2048
	global_store_short_d16_hi v65, v204, s[34:35] offset:2176
	global_store_short v65, v205, s[34:35] offset:2304
	global_store_short_d16_hi v65, v205, s[34:35] offset:2432
	s_waitcnt lgkmcnt(4)
	v_sub_f32_e32 v200, v60, v46
	v_sub_f32_e32 v201, v61, v46
	v_sub_f32_e32 v202, v62, v46
	v_sub_f32_e32 v203, v63, v46
	v_mul_f32_e32 v200, 0x3fb8aa3b, v200
	v_mul_f32_e32 v201, 0x3fb8aa3b, v201
	v_mul_f32_e32 v202, 0x3fb8aa3b, v202
	v_mul_f32_e32 v203, 0x3fb8aa3b, v203
	v_exp_f32_e32 v200, v200
	v_exp_f32_e32 v201, v201
	v_exp_f32_e32 v202, v202
	v_exp_f32_e32 v203, v203
	v_cmp_ge_i32_e64 s[28:29], 24, v67
	v_cmp_ge_i32_e64 s[36:37], 25, v67
	v_cmp_ge_i32_e64 s[40:41], 26, v67
	v_cmp_ge_i32_e64 s[46:47], 27, v67
	v_mul_f32_e32 v200, v12, v200
	v_mul_f32_e32 v201, v13, v201
	v_mul_f32_e32 v202, v14, v202
	v_mul_f32_e32 v203, v15, v203
	v_cndmask_b32_e64 v200, 0, v200, s[28:29]
	v_cndmask_b32_e64 v201, 0, v201, s[36:37]
	v_cndmask_b32_e64 v202, 0, v202, s[40:41]
	v_cndmask_b32_e64 v203, 0, v203, s[46:47]
	v_cvt_pk_bf16_f32 v204, v200, v201
	v_cvt_pk_bf16_f32 v205, v202, v203
	global_store_short v65, v204, s[34:35] offset:3072
	global_store_short_d16_hi v65, v204, s[34:35] offset:3200
	global_store_short v65, v205, s[34:35] offset:3328
	global_store_short_d16_hi v65, v205, s[34:35] offset:3456
	s_branch .Lkk_end
.Lkk_p0:
	s_waitcnt lgkmcnt(3)
	v_sub_f32_e32 v200, v48, v46
	v_sub_f32_e32 v201, v49, v46
	v_sub_f32_e32 v202, v50, v46
	v_sub_f32_e32 v203, v51, v46
	v_mul_f32_e32 v200, 0x3fb8aa3b, v200
	v_mul_f32_e32 v201, 0x3fb8aa3b, v201
	v_mul_f32_e32 v202, 0x3fb8aa3b, v202
	v_mul_f32_e32 v203, 0x3fb8aa3b, v203
	v_exp_f32_e32 v200, v200
	v_exp_f32_e32 v201, v201
	v_exp_f32_e32 v202, v202
	v_exp_f32_e32 v203, v203
	v_cmp_gt_i32_e64 s[28:29], 0, v67
	v_cmp_gt_i32_e64 s[36:37], 1, v67
	v_cmp_gt_i32_e64 s[40:41], 2, v67
	v_cmp_gt_i32_e64 s[46:47], 3, v67
	v_mul_f32_e32 v204, v0, v184
	v_mul_f32_e32 v205, v1, v185
	v_mul_f32_e32 v206, v2, v186
	v_mul_f32_e32 v207, v3, v187
	v_mul_f32_e32 v200, v200, v204
	v_mul_f32_e32 v201, v201, v205
	v_mul_f32_e32 v202, v202, v206
	v_mul_f32_e32 v203, v203, v207
	v_cndmask_b32_e64 v200, 0, v200, s[28:29]
	v_cndmask_b32_e64 v201, 0, v201, s[36:37]
	v_cndmask_b32_e64 v202, 0, v202, s[40:41]
	v_cndmask_b32_e64 v203, 0, v203, s[46:47]
	ds_write_b32 v66, v200 offset:49920
	ds_write_b32 v66, v201 offset:50176
	ds_write_b32 v66, v202 offset:50432
	ds_write_b32 v66, v203 offset:50688
	s_waitcnt lgkmcnt(6)
	v_sub_f32_e32 v200, v52, v46
	v_sub_f32_e32 v201, v53, v46
	v_sub_f32_e32 v202, v54, v46
	v_sub_f32_e32 v203, v55, v46
	v_mul_f32_e32 v200, 0x3fb8aa3b, v200
	v_mul_f32_e32 v201, 0x3fb8aa3b, v201
	v_mul_f32_e32 v202, 0x3fb8aa3b, v202
	v_mul_f32_e32 v203, 0x3fb8aa3b, v203
	v_exp_f32_e32 v200, v200
	v_exp_f32_e32 v201, v201
	v_exp_f32_e32 v202, v202
	v_exp_f32_e32 v203, v203
	v_cmp_gt_i32_e64 s[28:29], 8, v67
	v_cmp_gt_i32_e64 s[36:37], 9, v67
	v_cmp_gt_i32_e64 s[40:41], 10, v67
	v_cmp_gt_i32_e64 s[46:47], 11, v67
	v_mul_f32_e32 v204, v4, v188
	v_mul_f32_e32 v205, v5, v189
	v_mul_f32_e32 v206, v6, v190
	v_mul_f32_e32 v207, v7, v191
	v_mul_f32_e32 v200, v200, v204
	v_mul_f32_e32 v201, v201, v205
	v_mul_f32_e32 v202, v202, v206
	v_mul_f32_e32 v203, v203, v207
	v_cndmask_b32_e64 v200, 0, v200, s[28:29]
	v_cndmask_b32_e64 v201, 0, v201, s[36:37]
	v_cndmask_b32_e64 v202, 0, v202, s[40:41]
	v_cndmask_b32_e64 v203, 0, v203, s[46:47]
	ds_write_b32 v66, v200 offset:51968
	ds_write_b32 v66, v201 offset:52224
	ds_write_b32 v66, v202 offset:52480
	ds_write_b32 v66, v203 offset:52736
	s_waitcnt lgkmcnt(9)
	v_sub_f32_e32 v200, v56, v46
	v_sub_f32_e32 v201, v57, v46
	v_sub_f32_e32 v202, v58, v46
	v_sub_f32_e32 v203, v59, v46
	v_mul_f32_e32 v200, 0x3fb8aa3b, v200
	v_mul_f32_e32 v201, 0x3fb8aa3b, v201
	v_mul_f32_e32 v202, 0x3fb8aa3b, v202
	v_mul_f32_e32 v203, 0x3fb8aa3b, v203
	v_exp_f32_e32 v200, v200
	v_exp_f32_e32 v201, v201
	v_exp_f32_e32 v202, v202
	v_exp_f32_e32 v203, v203
	v_cmp_gt_i32_e64 s[28:29], 16, v67
	v_cmp_gt_i32_e64 s[36:37], 17, v67
	v_cmp_gt_i32_e64 s[40:41], 18, v67
	v_cmp_gt_i32_e64 s[46:47], 19, v67
	v_mul_f32_e32 v204, v8, v192
	v_mul_f32_e32 v205, v9, v193
	v_mul_f32_e32 v206, v10, v194
	v_mul_f32_e32 v207, v11, v195
	v_mul_f32_e32 v200, v200, v204
	v_mul_f32_e32 v201, v201, v205
	v_mul_f32_e32 v202, v202, v206
	v_mul_f32_e32 v203, v203, v207
	v_cndmask_b32_e64 v200, 0, v200, s[28:29]
	v_cndmask_b32_e64 v201, 0, v201, s[36:37]
	v_cndmask_b32_e64 v202, 0, v202, s[40:41]
	v_cndmask_b32_e64 v203, 0, v203, s[46:47]
	ds_write_b32 v66, v200 offset:54016
	ds_write_b32 v66, v201 offset:54272
	ds_write_b32 v66, v202 offset:54528
	ds_write_b32 v66, v203 offset:54784
	s_waitcnt lgkmcnt(12)
	v_sub_f32_e32 v200, v60, v46
	v_sub_f32_e32 v201, v61, v46
	v_sub_f32_e32 v202, v62, v46
	v_sub_f32_e32 v203, v63, v46
	v_mul_f32_e32 v200, 0x3fb8aa3b, v200
	v_mul_f32_e32 v201, 0x3fb8aa3b, v201
	v_mul_f32_e32 v202, 0x3fb8aa3b, v202
	v_mul_f32_e32 v203, 0x3fb8aa3b, v203
	v_exp_f32_e32 v200, v200
	v_exp_f32_e32 v201, v201
	v_exp_f32_e32 v202, v202
	v_exp_f32_e32 v203, v203
	v_cmp_gt_i32_e64 s[28:29], 24, v67
	v_cmp_gt_i32_e64 s[36:37], 25, v67
	v_cmp_gt_i32_e64 s[40:41], 26, v67
	v_cmp_gt_i32_e64 s[46:47], 27, v67
	v_mul_f32_e32 v204, v12, v196
	v_mul_f32_e32 v205, v13, v197
	v_mul_f32_e32 v206, v14, v198
	v_mul_f32_e32 v207, v15, v199
	v_mul_f32_e32 v200, v200, v204
	v_mul_f32_e32 v201, v201, v205
	v_mul_f32_e32 v202, v202, v206
	v_mul_f32_e32 v203, v203, v207
	v_cndmask_b32_e64 v200, 0, v200, s[28:29]
	v_cndmask_b32_e64 v201, 0, v201, s[36:37]
	v_cndmask_b32_e64 v202, 0, v202, s[40:41]
	v_cndmask_b32_e64 v203, 0, v203, s[46:47]
	ds_write_b32 v66, v200 offset:56064
	ds_write_b32 v66, v201 offset:56320
	ds_write_b32 v66, v202 offset:56576
	ds_write_b32 v66, v203 offset:56832
.Lkk_end:
	s_waitcnt lgkmcnt(0)
	s_barrier
	s_and_saveexec_b64 s[0:1], s[22:23]
	s_cbranch_execz .LBB0_3018
	ds_read_b32 v2, v91
	s_and_saveexec_b64 s[28:29], s[16:17]
	s_xor_b64 s[28:29], exec, s[28:29]
	s_cbranch_execz .LBB0_3013
	ds_read_b32 v8, v92 offset:16640
	ds_read_b128 v[4:7], v79
	v_mov_b32_e32 v41, v21
	v_lshl_add_u64 v[0:1], s[30:31], 0, v[40:41]
	s_mov_b64 s[34:35], 0x8000
	v_lshl_add_u64 v[0:1], v[0:1], 0, s[34:35]
	s_waitcnt lgkmcnt(0)
	v_sub_f32_e32 v3, v2, v4
	v_mul_f32_e32 v3, 0x3fb8aa3b, v3
	v_exp_f32_e32 v4, v3
	v_add_u32_e32 v3, 0x4000, v93
	ds_read2_b32 v[10:11], v3 offset0:64 offset1:129
	v_sub_f32_e32 v3, v2, v5
	v_mul_f32_e32 v3, 0x3fb8aa3b, v3
	v_exp_f32_e32 v5, v3
	v_sub_f32_e32 v3, v2, v6
	s_waitcnt lgkmcnt(0)
	v_mov_b32_e32 v9, v10
	v_mul_f32_e32 v3, 0x3fb8aa3b, v3
	v_pk_mul_f32 v[8:9], v[8:9], v[4:5]
	v_exp_f32_e32 v4, v3
	v_add_u32_e32 v3, 0x4200, v93
	ds_read2_b32 v[12:13], v3 offset0:66 offset1:131
	v_sub_f32_e32 v3, v2, v7
	v_mul_f32_e32 v3, 0x3fb8aa3b, v3
	v_exp_f32_e32 v5, v3
	v_mov_b32_e32 v6, v11
	s_waitcnt lgkmcnt(0)
	v_mov_b32_e32 v7, v12
	ds_read_b32 v45, v93 offset:18200
	v_pk_mul_f32 v[10:11], v[6:7], v[4:5]
	ds_read_b128 v[4:7], v80
	v_mov_b32_e32 v12, v13
	v_mov_b32_e32 v43, v21
	s_waitcnt lgkmcnt(0)
	v_sub_f32_e32 v3, v2, v4
	v_mul_f32_e32 v3, 0x3fb8aa3b, v3
	v_exp_f32_e32 v4, v3
	v_add_u32_e32 v3, 0x4400, v93
	ds_read2_b32 v[14:15], v3 offset0:68 offset1:133
	v_sub_f32_e32 v3, v2, v5
	v_mul_f32_e32 v3, 0x3fb8aa3b, v3
	v_exp_f32_e32 v5, v3
	v_sub_f32_e32 v3, v2, v6
	s_waitcnt lgkmcnt(0)
	v_mov_b32_e32 v13, v14
	v_mul_f32_e32 v3, 0x3fb8aa3b, v3
	v_pk_mul_f32 v[12:13], v[12:13], v[4:5]
	v_exp_f32_e32 v4, v3
	v_sub_f32_e32 v3, v2, v7
	v_mul_f32_e32 v3, 0x3fb8aa3b, v3
	v_exp_f32_e32 v5, v3
	v_mov_b32_e32 v44, v15
	v_cvt_pk_bf16_f32 v6, v12, v13
	v_add_u32_e32 v3, 0x4000, v94
	v_pk_mul_f32 v[14:15], v[44:45], v[4:5]
	v_cvt_pk_bf16_f32 v4, v8, v9
	v_cvt_pk_bf16_f32 v5, v10, v11
	v_cvt_pk_bf16_f32 v7, v14, v15
	v_lshl_add_u64 v[8:9], v[22:23], 1, v[0:1]
	global_store_dwordx4 v[8:9], v[4:7], off
	ds_read2_b32 v[8:9], v3 offset0:64 offset1:129
	ds_read_b128 v[4:7], v82
	v_lshl_add_u64 v[0:1], v[0:1], 0, v[42:43]
	s_waitcnt lgkmcnt(0)
	v_sub_f32_e32 v3, v2, v4
	v_mul_f32_e32 v3, 0x3fb8aa3b, v3
	v_exp_f32_e32 v4, v3
	v_sub_f32_e32 v3, v2, v5
	v_mul_f32_e32 v3, 0x3fb8aa3b, v3
	v_exp_f32_e32 v5, v3
	v_add_u32_e32 v3, 0x4200, v94
	v_pk_mul_f32 v[8:9], v[8:9], v[4:5]
	ds_read2_b32 v[4:5], v3 offset0:66 offset1:131
	v_sub_f32_e32 v3, v2, v6
	v_mul_f32_e32 v3, 0x3fb8aa3b, v3
	v_exp_f32_e32 v6, v3
	v_sub_f32_e32 v3, v2, v7
	v_mul_f32_e32 v3, 0x3fb8aa3b, v3
	v_exp_f32_e32 v7, v3
	v_add_u32_e32 v3, 0x4400, v94
	s_waitcnt lgkmcnt(0)
	v_pk_mul_f32 v[10:11], v[4:5], v[6:7]
	ds_read2_b32 v[12:13], v3 offset0:68 offset1:133
	ds_read_b128 v[4:7], v83
	s_waitcnt lgkmcnt(0)
	v_sub_f32_e32 v3, v2, v4
	v_mul_f32_e32 v3, 0x3fb8aa3b, v3
	v_exp_f32_e32 v4, v3
	v_sub_f32_e32 v3, v2, v5
	v_mul_f32_e32 v3, 0x3fb8aa3b, v3
	v_exp_f32_e32 v5, v3
	v_add_u32_e32 v3, 0x4600, v94
	v_pk_mul_f32 v[12:13], v[12:13], v[4:5]
	ds_read2_b32 v[4:5], v3 offset0:70 offset1:135
	v_sub_f32_e32 v3, v2, v6
	v_mul_f32_e32 v3, 0x3fb8aa3b, v3
	v_exp_f32_e32 v6, v3
	v_sub_f32_e32 v3, v2, v7
	v_mul_f32_e32 v3, 0x3fb8aa3b, v3
	v_exp_f32_e32 v7, v3
	v_add_u32_e32 v3, 0x4800, v94
	s_waitcnt lgkmcnt(0)
	v_pk_mul_f32 v[14:15], v[4:5], v[6:7]
	v_cvt_pk_bf16_f32 v4, v8, v9
	v_cvt_pk_bf16_f32 v5, v10, v11
	v_cvt_pk_bf16_f32 v6, v12, v13
	v_cvt_pk_bf16_f32 v7, v14, v15
	global_store_dwordx4 v[0:1], v[4:7], off offset:-240
	ds_read2_b32 v[8:9], v3 offset0:72 offset1:137
	ds_read_b128 v[4:7], v84
	s_waitcnt lgkmcnt(0)
	v_sub_f32_e32 v3, v2, v4
	v_mul_f32_e32 v3, 0x3fb8aa3b, v3
	v_exp_f32_e32 v4, v3
	v_sub_f32_e32 v3, v2, v5
	v_mul_f32_e32 v3, 0x3fb8aa3b, v3
	v_exp_f32_e32 v5, v3
	v_add_u32_e32 v3, 0x4a00, v94
	v_pk_mul_f32 v[8:9], v[8:9], v[4:5]
	ds_read2_b32 v[4:5], v3 offset0:74 offset1:139
	v_sub_f32_e32 v3, v2, v6
	v_mul_f32_e32 v3, 0x3fb8aa3b, v3
	v_exp_f32_e32 v6, v3
	v_sub_f32_e32 v3, v2, v7
	v_mul_f32_e32 v3, 0x3fb8aa3b, v3
	v_exp_f32_e32 v7, v3
	v_add_u32_e32 v3, 0x4c00, v94
	s_waitcnt lgkmcnt(0)
	v_pk_mul_f32 v[10:11], v[4:5], v[6:7]
	ds_read2_b32 v[12:13], v3 offset0:76 offset1:141
	ds_read_b128 v[4:7], v85
	s_waitcnt lgkmcnt(0)
	v_sub_f32_e32 v3, v2, v4
	v_mul_f32_e32 v3, 0x3fb8aa3b, v3
	v_exp_f32_e32 v4, v3
	v_sub_f32_e32 v3, v2, v5
	v_mul_f32_e32 v3, 0x3fb8aa3b, v3
	v_exp_f32_e32 v5, v3
	v_add_u32_e32 v3, 0x4e00, v94
	v_pk_mul_f32 v[12:13], v[12:13], v[4:5]
	ds_read2_b32 v[4:5], v3 offset0:78 offset1:143
	v_sub_f32_e32 v3, v2, v6
	v_mul_f32_e32 v3, 0x3fb8aa3b, v3
	v_exp_f32_e32 v6, v3
	v_sub_f32_e32 v3, v2, v7
	v_mul_f32_e32 v3, 0x3fb8aa3b, v3
	v_exp_f32_e32 v7, v3
	v_add_u32_e32 v3, 0x5000, v94
	s_waitcnt lgkmcnt(0)
	v_pk_mul_f32 v[14:15], v[4:5], v[6:7]
	v_cvt_pk_bf16_f32 v4, v8, v9
	v_cvt_pk_bf16_f32 v5, v10, v11
	v_cvt_pk_bf16_f32 v6, v12, v13
	v_cvt_pk_bf16_f32 v7, v14, v15
	global_store_dwordx4 v[0:1], v[4:7], off offset:-224
	ds_read2_b32 v[8:9], v3 offset0:80 offset1:145
	ds_read_b128 v[4:7], v86
	s_waitcnt lgkmcnt(0)
	v_sub_f32_e32 v3, v2, v4
	v_mul_f32_e32 v3, 0x3fb8aa3b, v3
	v_exp_f32_e32 v4, v3
	v_sub_f32_e32 v3, v2, v5
	v_mul_f32_e32 v3, 0x3fb8aa3b, v3
	v_exp_f32_e32 v5, v3
	v_add_u32_e32 v3, 0x5200, v94
	v_pk_mul_f32 v[8:9], v[8:9], v[4:5]
	ds_read2_b32 v[4:5], v3 offset0:82 offset1:147
	v_sub_f32_e32 v3, v2, v6
	v_mul_f32_e32 v3, 0x3fb8aa3b, v3
	v_exp_f32_e32 v6, v3
	v_sub_f32_e32 v3, v2, v7
	v_mul_f32_e32 v3, 0x3fb8aa3b, v3
	v_exp_f32_e32 v7, v3
	v_add_u32_e32 v3, 0x5400, v94
	s_waitcnt lgkmcnt(0)
	v_pk_mul_f32 v[10:11], v[4:5], v[6:7]
	ds_read2_b32 v[12:13], v3 offset0:84 offset1:149
	ds_read_b128 v[4:7], v87
	s_waitcnt lgkmcnt(0)
	v_sub_f32_e32 v3, v2, v4
	v_mul_f32_e32 v3, 0x3fb8aa3b, v3
	v_exp_f32_e32 v4, v3
	v_sub_f32_e32 v3, v2, v5
	v_mul_f32_e32 v3, 0x3fb8aa3b, v3
	v_exp_f32_e32 v5, v3
	v_add_u32_e32 v3, 0x5600, v94
	v_pk_mul_f32 v[12:13], v[12:13], v[4:5]
	ds_read2_b32 v[4:5], v3 offset0:86 offset1:151
	v_sub_f32_e32 v3, v2, v6
	v_mul_f32_e32 v3, 0x3fb8aa3b, v3
	v_exp_f32_e32 v6, v3
	v_sub_f32_e32 v3, v2, v7
	v_mul_f32_e32 v3, 0x3fb8aa3b, v3
	v_exp_f32_e32 v7, v3
	s_waitcnt lgkmcnt(0)
	v_pk_mul_f32 v[14:15], v[4:5], v[6:7]
	v_cvt_pk_bf16_f32 v4, v8, v9
	v_cvt_pk_bf16_f32 v5, v10, v11
	v_cvt_pk_bf16_f32 v6, v12, v13
	v_cvt_pk_bf16_f32 v7, v14, v15
	global_store_dwordx4 v[0:1], v[4:7], off offset:-208
